# SGU: later tasks' row loads of a head issued with the first task's loads (spare registers), copied in place
# speedup vs baseline: 1.0001x; 1.0001x over previous
.LBB0_124:
	v_lshl_add_u64 v[2:3], v[116:117], 0, s[74:75]
	flat_load_dwordx4 v[14:17], v[2:3]
	v_lshl_add_u64 v[248:249], v[114:115], 0, s[74:75]
	global_load_dwordx4 v[154:157], v[248:249], off
	v_lshl_add_u64 v[248:249], v[112:113], 0, s[74:75]
	global_load_dwordx4 v[210:213], v[248:249], off
	v_lshl_add_u64 v[248:249], v[110:111], 0, s[74:75]
	global_load_dwordx4 v[222:225], v[248:249], off
	v_lshl_add_u64 v[6:7], v[138:139], 0, s[72:73]
	v_lshl_add_u64 v[22:23], v[130:131], 0, s[72:73]
	ds_read_b64 v[10:11], v176
	s_waitcnt lgkmcnt(0)
	global_load_dwordx4 v[2:5], v[6:7], off
	global_load_dwordx4 v[18:21], v[6:7], off offset:-16
	s_nop 0
	global_load_dwordx4 v[6:9], v[22:23], off
	s_nop 0
	global_load_dwordx4 v[22:25], v[22:23], off offset:-16
	v_lshl_add_u64 v[12:13], v[122:123], 0, s[74:75]
	s_mov_b32 s49, 0x9c00000
	v_add_co_u32_e32 v26, vcc, s49, v12
	s_mov_b32 s49, 0x9c01000
	s_nop 0
	v_addc_co_u32_e32 v27, vcc, 0, v13, vcc
	v_add_co_u32_e32 v28, vcc, s49, v12
	s_mov_b32 s49, 0x9c03000
	s_nop 0
	v_addc_co_u32_e32 v29, vcc, 0, v13, vcc
	v_add_co_u32_e32 v30, vcc, s49, v12
	s_mov_b32 s49, 0x9c04000
	s_nop 0
	v_addc_co_u32_e32 v31, vcc, 0, v13, vcc
	v_add_co_u32_e32 v12, vcc, s49, v12
	s_bitcmp1_b32 s48, 0
	s_nop 0
	v_addc_co_u32_e32 v13, vcc, 0, v13, vcc
	flat_load_ushort v208, v[26:27]
	flat_load_ushort v207, v[26:27] offset:32
	flat_load_ushort v206, v[26:27] offset:64
	flat_load_ushort v205, v[26:27] offset:96
	flat_load_ushort v204, v[26:27] offset:128
	flat_load_ushort v203, v[26:27] offset:160
	flat_load_ushort v202, v[26:27] offset:192
	flat_load_ushort v201, v[26:27] offset:224
	flat_load_ushort v200, v[28:29] offset:2048
	flat_load_ushort v199, v[28:29] offset:2080
	flat_load_ushort v198, v[28:29] offset:2112
	flat_load_ushort v197, v[28:29] offset:2144
	flat_load_ushort v196, v[28:29] offset:2176
	flat_load_ushort v195, v[28:29] offset:2208
	flat_load_ushort v194, v[28:29] offset:2240
	flat_load_ushort v193, v[28:29] offset:2272
	flat_load_ushort v192, v[30:31]
	flat_load_ushort v191, v[30:31] offset:32
	flat_load_ushort v190, v[30:31] offset:64
	flat_load_ushort v189, v[30:31] offset:96
	flat_load_ushort v188, v[30:31] offset:128
	flat_load_ushort v187, v[30:31] offset:160
	flat_load_ushort v186, v[30:31] offset:192
	flat_load_ushort v185, v[30:31] offset:224
	flat_load_ushort v184, v[12:13] offset:2048
	flat_load_ushort v183, v[12:13] offset:2080
	flat_load_ushort v182, v[12:13] offset:2112
	flat_load_ushort v181, v[12:13] offset:2144
	flat_load_ushort v180, v[12:13] offset:2176
	flat_load_ushort v179, v[12:13] offset:2208
	flat_load_ushort v178, v[12:13] offset:2240
	flat_load_ushort v177, v[12:13] offset:2272
	s_cselect_b32 s37, 0x8800, 0
	s_add_i32 s37, s37, 0
	v_lshl_add_u32 v12, v0, 1, s37
	v_add_u32_e32 v13, v12, v164
	s_andn2_b64 vcc, exec, s[30:31]
	v_mov_b32_e32 v33, 0
	s_waitcnt vmcnt(0)
	v_lshlrev_b32_e32 v26, 16, v14
	v_and_b32_e32 v14, 0xffff0000, v14
	v_mul_f32_e32 v31, 0x3d372713, v14
	v_mul_f32_e32 v31, v31, v14
	v_mul_f32_e32 v30, 0x3d372713, v26
	v_fma_f32 v31, v31, v14, v14
	v_mul_f32_e32 v30, v30, v26
	v_mul_f32_e32 v31, 0xbfcc422a, v31
	v_fma_f32 v30, v30, v26, v26
	v_mul_f32_e32 v31, 0x3fb8aa3b, v31
	v_mul_f32_e32 v30, 0xbfcc422a, v30
	v_exp_f32_e32 v31, v31
	v_mul_f32_e32 v30, 0x3fb8aa3b, v30
	v_exp_f32_e32 v30, v30
	v_lshlrev_b32_e32 v27, 16, v15
	v_add_f32_e32 v31, 1.0, v31
	v_rcp_f32_e32 v31, v31
	v_mul_f32_e32 v32, 0x3d372713, v27
	v_add_f32_e32 v30, 1.0, v30
	v_mul_f32_e32 v32, v32, v27
	v_rcp_f32_e32 v30, v30
	v_fma_f32 v32, v32, v27, v27
	v_mul_f32_e32 v32, 0xbfcc422a, v32
	v_fma_f32 v14, v31, v14, -v10
	v_and_b32_e32 v15, 0xffff0000, v15
	v_mul_f32_e32 v32, 0x3fb8aa3b, v32
	v_mul_f32_e32 v14, v11, v14
	v_exp_f32_e32 v32, v32
	v_fma_f32 v26, v30, v26, -v10
	v_fma_f32 v14, v19, v14, v23
	v_mul_f32_e32 v19, 0x3d372713, v15
	v_mul_f32_e32 v26, v11, v26
	v_mul_f32_e32 v19, v19, v15
	v_fma_f32 v18, v18, v26, v22
	v_fma_f32 v19, v19, v15, v15
	v_cvt_pk_bf16_f32 v18, v18, s0
	v_mul_f32_e32 v19, 0xbfcc422a, v19
	ds_write_b16 v13, v18 offset:1024
	v_add_f32_e32 v18, 1.0, v32
	v_mul_f32_e32 v19, 0x3fb8aa3b, v19
	v_rcp_f32_e32 v18, v18
	v_exp_f32_e32 v19, v19
	v_cvt_pk_bf16_f32 v14, v14, s0
	ds_write_b16 v13, v14 offset:1296
	v_fma_f32 v14, v18, v27, -v10
	v_add_f32_e32 v18, 1.0, v19
	v_rcp_f32_e32 v18, v18
	v_mul_f32_e32 v14, v11, v14
	v_fma_f32 v14, v20, v14, v24
	v_lshlrev_b32_e32 v28, 16, v16
	v_cvt_pk_bf16_f32 v14, v14, s0
	ds_write_b16 v13, v14 offset:1568
	v_fma_f32 v14, v18, v15, -v10
	v_mul_f32_e32 v15, 0x3d372713, v28
	v_mul_f32_e32 v15, v15, v28
	v_fma_f32 v15, v15, v28, v28
	v_mul_f32_e32 v15, 0xbfcc422a, v15
	v_mul_f32_e32 v15, 0x3fb8aa3b, v15
	v_exp_f32_e32 v15, v15
	v_and_b32_e32 v16, 0xffff0000, v16
	v_mul_f32_e32 v18, 0x3d372713, v16
	v_mul_f32_e32 v18, v18, v16
	v_add_f32_e32 v15, 1.0, v15
	v_rcp_f32_e32 v15, v15
	v_mul_f32_e32 v14, v11, v14
	v_fma_f32 v18, v18, v16, v16
	v_fmac_f32_e32 v25, v21, v14
	v_mul_f32_e32 v18, 0xbfcc422a, v18
	v_cvt_pk_bf16_f32 v14, v25, s0
	v_mul_f32_e32 v18, 0x3fb8aa3b, v18
	v_exp_f32_e32 v18, v18
	ds_write_b16 v13, v14 offset:1840
	v_fma_f32 v14, v15, v28, -v10
	v_lshlrev_b32_e32 v29, 16, v17
	v_mul_f32_e32 v14, v11, v14
	v_fma_f32 v2, v2, v14, v6
	v_mul_f32_e32 v6, 0x3d372713, v29
	v_mul_f32_e32 v6, v6, v29
	v_add_f32_e32 v15, 1.0, v18
	v_fma_f32 v6, v6, v29, v29
	v_rcp_f32_e32 v15, v15
	v_mul_f32_e32 v6, 0xbfcc422a, v6
	v_mul_f32_e32 v6, 0x3fb8aa3b, v6
	v_exp_f32_e32 v6, v6
	v_cvt_pk_bf16_f32 v2, v2, s0
	ds_write_b16 v13, v2 offset:2112
	v_fma_f32 v2, v15, v16, -v10
	v_and_b32_e32 v17, 0xffff0000, v17
	v_mul_f32_e32 v2, v11, v2
	v_fma_f32 v2, v3, v2, v7
	v_add_f32_e32 v3, 1.0, v6
	v_mul_f32_e32 v6, 0x3d372713, v17
	v_mul_f32_e32 v6, v6, v17
	v_fma_f32 v6, v6, v17, v17
	v_mul_f32_e32 v6, 0xbfcc422a, v6
	v_mul_f32_e32 v6, 0x3fb8aa3b, v6
	v_rcp_f32_e32 v3, v3
	v_exp_f32_e32 v6, v6
	v_cvt_pk_bf16_f32 v2, v2, s0
	ds_write_b16 v13, v2 offset:2384
	v_fma_f32 v2, v3, v29, -v10
	v_add_f32_e32 v3, 1.0, v6
	v_rcp_f32_e32 v3, v3
	v_mul_f32_e32 v2, v11, v2
	v_fma_f32 v2, v4, v2, v8
	v_cvt_pk_bf16_f32 v2, v2, s0
	ds_write_b16 v13, v2 offset:2656
	v_fma_f32 v2, v3, v17, -v10
	v_mul_f32_e32 v2, v11, v2
	v_fmac_f32_e32 v9, v5, v2
	v_cvt_pk_bf16_f32 v2, v9, s0
	v_add_u32_e32 v3, v12, v165
	ds_write_b16 v3, v2 offset:1024
	v_mov_b64_e32 v[2:3], v[154:155]
	v_mov_b64_e32 v[4:5], v[156:157]
	v_lshl_add_u64 v[18:19], v[136:137], 0, s[72:73]
	v_lshl_add_u64 v[22:23], v[128:129], 0, s[72:73]
	global_load_dwordx4 v[6:9], v[22:23], off offset:-16
	global_load_dwordx4 v[14:17], v[18:19], off offset:-16
	s_nop 0
	global_load_dwordx4 v[18:21], v[18:19], off
	s_nop 0
	global_load_dwordx4 v[22:25], v[22:23], off
	v_mov_b32_e32 v31, 0
	v_mov_b32_e32 v32, 0
	s_waitcnt vmcnt(0) lgkmcnt(0)
	v_lshlrev_b32_e32 v13, 16, v2
	v_mul_f32_e32 v28, 0x3d372713, v13
	v_mul_f32_e32 v28, v28, v13
	v_fma_f32 v28, v28, v13, v13
	v_mul_f32_e32 v28, 0xbfcc422a, v28
	v_mul_f32_e32 v28, 0x3fb8aa3b, v28
	v_exp_f32_e32 v28, v28
	v_and_b32_e32 v2, 0xffff0000, v2
	v_mul_f32_e32 v30, 0x3d372713, v2
	v_mul_f32_e32 v30, v30, v2
	v_add_f32_e32 v28, 1.0, v28
	v_fma_f32 v30, v30, v2, v2
	v_rcp_f32_e32 v28, v28
	v_mul_f32_e32 v30, 0xbfcc422a, v30
	v_mul_f32_e32 v30, 0x3fb8aa3b, v30
	v_exp_f32_e32 v30, v30
	v_fma_f32 v13, v28, v13, -v10
	v_mul_f32_e32 v13, v11, v13
	v_fma_f32 v6, v14, v13, v6
	v_add_f32_e32 v13, 1.0, v30
	v_lshlrev_b32_e32 v26, 16, v3
	v_rcp_f32_e32 v13, v13
	v_cvt_pk_bf16_f32 v6, v6, s0
	v_add_u32_e32 v14, v12, v166
	ds_write_b16 v14, v6 offset:1024
	v_mul_f32_e32 v6, 0x3d372713, v26
	v_mul_f32_e32 v6, v6, v26
	v_fma_f32 v6, v6, v26, v26
	v_fma_f32 v2, v13, v2, -v10
	v_mul_f32_e32 v6, 0xbfcc422a, v6
	v_and_b32_e32 v3, 0xffff0000, v3
	v_mul_f32_e32 v6, 0x3fb8aa3b, v6
	v_mul_f32_e32 v2, v11, v2
	v_exp_f32_e32 v6, v6
	v_fma_f32 v2, v15, v2, v7
	v_mul_f32_e32 v7, 0x3d372713, v3
	v_mul_f32_e32 v7, v7, v3
	v_fma_f32 v7, v7, v3, v3
	v_mul_f32_e32 v7, 0xbfcc422a, v7
	v_add_f32_e32 v6, 1.0, v6
	v_mul_f32_e32 v7, 0x3fb8aa3b, v7
	v_rcp_f32_e32 v6, v6
	v_exp_f32_e32 v7, v7
	v_cvt_pk_bf16_f32 v2, v2, s0
	ds_write_b16 v14, v2 offset:1296
	v_fma_f32 v2, v6, v26, -v10
	v_add_f32_e32 v6, 1.0, v7
	v_rcp_f32_e32 v6, v6
	v_mul_f32_e32 v2, v11, v2
	v_fma_f32 v2, v16, v2, v8
	v_lshlrev_b32_e32 v27, 16, v4
	v_cvt_pk_bf16_f32 v2, v2, s0
	ds_write_b16 v14, v2 offset:1568
	v_fma_f32 v2, v6, v3, -v10
	v_mul_f32_e32 v3, 0x3d372713, v27
	v_mul_f32_e32 v3, v3, v27
	v_fma_f32 v3, v3, v27, v27
	v_mul_f32_e32 v3, 0xbfcc422a, v3
	v_and_b32_e32 v4, 0xffff0000, v4
	v_mul_f32_e32 v3, 0x3fb8aa3b, v3
	v_exp_f32_e32 v3, v3
	v_mul_f32_e32 v6, 0x3d372713, v4
	v_mul_f32_e32 v6, v6, v4
	v_fma_f32 v6, v6, v4, v4
	v_mul_f32_e32 v6, 0xbfcc422a, v6
	v_add_f32_e32 v3, 1.0, v3
	v_mul_f32_e32 v6, 0x3fb8aa3b, v6
	v_rcp_f32_e32 v3, v3
	v_exp_f32_e32 v6, v6
	v_mul_f32_e32 v2, v11, v2
	v_fmac_f32_e32 v9, v17, v2
	v_cvt_pk_bf16_f32 v2, v9, s0
	ds_write_b16 v14, v2 offset:1840
	v_fma_f32 v2, v3, v27, -v10
	v_add_f32_e32 v3, 1.0, v6
	v_rcp_f32_e32 v3, v3
	v_mul_f32_e32 v2, v11, v2
	v_fma_f32 v2, v18, v2, v22
	v_lshlrev_b32_e32 v29, 16, v5
	v_cvt_pk_bf16_f32 v2, v2, s0
	ds_write_b16 v14, v2 offset:2112
	v_fma_f32 v2, v3, v4, -v10
	v_mul_f32_e32 v3, 0x3d372713, v29
	v_mul_f32_e32 v3, v3, v29
	v_fma_f32 v3, v3, v29, v29
	v_mul_f32_e32 v3, 0xbfcc422a, v3
	v_and_b32_e32 v5, 0xffff0000, v5
	v_mul_f32_e32 v3, 0x3fb8aa3b, v3
	v_exp_f32_e32 v3, v3
	v_mul_f32_e32 v4, 0x3d372713, v5
	v_mul_f32_e32 v4, v4, v5
	v_fma_f32 v4, v4, v5, v5
	v_mul_f32_e32 v4, 0xbfcc422a, v4
	v_add_f32_e32 v3, 1.0, v3
	v_mul_f32_e32 v4, 0x3fb8aa3b, v4
	v_rcp_f32_e32 v3, v3
	v_exp_f32_e32 v4, v4
	v_mul_f32_e32 v2, v11, v2
	v_fma_f32 v2, v19, v2, v23
	v_cvt_pk_bf16_f32 v2, v2, s0
	ds_write_b16 v14, v2 offset:2384
	v_fma_f32 v2, v3, v29, -v10
	v_add_f32_e32 v3, 1.0, v4
	v_rcp_f32_e32 v3, v3
	v_mul_f32_e32 v2, v11, v2
	v_fma_f32 v2, v20, v2, v24
	v_cvt_pk_bf16_f32 v2, v2, s0
	ds_write_b16 v14, v2 offset:2656
	v_fma_f32 v2, v3, v5, -v10
	v_mul_f32_e32 v2, v11, v2
	v_fmac_f32_e32 v25, v21, v2
	v_cvt_pk_bf16_f32 v2, v25, s0
	v_add_u32_e32 v3, v12, v167
	ds_write_b16 v3, v2 offset:1024
	v_mov_b64_e32 v[2:3], v[210:211]
	v_mov_b64_e32 v[4:5], v[212:213]
	v_lshl_add_u64 v[18:19], v[134:135], 0, s[72:73]
	v_lshl_add_u64 v[22:23], v[126:127], 0, s[72:73]
	global_load_dwordx4 v[6:9], v[22:23], off offset:-16
	global_load_dwordx4 v[14:17], v[18:19], off offset:-16
	s_nop 0
	global_load_dwordx4 v[18:21], v[18:19], off
	s_nop 0
	global_load_dwordx4 v[22:25], v[22:23], off
	s_waitcnt vmcnt(0) lgkmcnt(0)
	v_lshlrev_b32_e32 v13, 16, v2
	v_mul_f32_e32 v28, 0x3d372713, v13
	v_mul_f32_e32 v28, v28, v13
	v_fma_f32 v28, v28, v13, v13
	v_mul_f32_e32 v28, 0xbfcc422a, v28
	v_mul_f32_e32 v28, 0x3fb8aa3b, v28
	v_exp_f32_e32 v28, v28
	v_and_b32_e32 v2, 0xffff0000, v2
	v_mul_f32_e32 v30, 0x3d372713, v2
	v_mul_f32_e32 v30, v30, v2
	v_add_f32_e32 v28, 1.0, v28
	v_fma_f32 v30, v30, v2, v2
	v_rcp_f32_e32 v28, v28
	v_mul_f32_e32 v30, 0xbfcc422a, v30
	v_mul_f32_e32 v30, 0x3fb8aa3b, v30
	v_exp_f32_e32 v30, v30
	v_fma_f32 v13, v28, v13, -v10
	v_mul_f32_e32 v13, v11, v13
	v_fma_f32 v6, v14, v13, v6
	v_add_f32_e32 v13, 1.0, v30
	v_lshlrev_b32_e32 v26, 16, v3
	v_rcp_f32_e32 v13, v13
	v_cvt_pk_bf16_f32 v6, v6, s0
	v_add_u32_e32 v14, v12, v168
	ds_write_b16 v14, v6 offset:1024
	v_mul_f32_e32 v6, 0x3d372713, v26
	v_mul_f32_e32 v6, v6, v26
	v_fma_f32 v6, v6, v26, v26
	v_fma_f32 v2, v13, v2, -v10
	v_mul_f32_e32 v6, 0xbfcc422a, v6
	v_and_b32_e32 v3, 0xffff0000, v3
	v_mul_f32_e32 v6, 0x3fb8aa3b, v6
	v_mul_f32_e32 v2, v11, v2
	v_exp_f32_e32 v6, v6
	v_fma_f32 v2, v15, v2, v7
	v_mul_f32_e32 v7, 0x3d372713, v3
	v_mul_f32_e32 v7, v7, v3
	v_fma_f32 v7, v7, v3, v3
	v_mul_f32_e32 v7, 0xbfcc422a, v7
	v_add_f32_e32 v6, 1.0, v6
	v_mul_f32_e32 v7, 0x3fb8aa3b, v7
	v_rcp_f32_e32 v6, v6
	v_exp_f32_e32 v7, v7
	v_cvt_pk_bf16_f32 v2, v2, s0
	ds_write_b16 v14, v2 offset:1296
	v_fma_f32 v2, v6, v26, -v10
	v_add_f32_e32 v6, 1.0, v7
	v_rcp_f32_e32 v6, v6
	v_mul_f32_e32 v2, v11, v2
	v_fma_f32 v2, v16, v2, v8
	v_lshlrev_b32_e32 v27, 16, v4
	v_cvt_pk_bf16_f32 v2, v2, s0
	ds_write_b16 v14, v2 offset:1568
	v_fma_f32 v2, v6, v3, -v10
	v_mul_f32_e32 v3, 0x3d372713, v27
	v_mul_f32_e32 v3, v3, v27
	v_fma_f32 v3, v3, v27, v27
	v_mul_f32_e32 v3, 0xbfcc422a, v3
	v_and_b32_e32 v4, 0xffff0000, v4
	v_mul_f32_e32 v3, 0x3fb8aa3b, v3
	v_exp_f32_e32 v3, v3
	v_mul_f32_e32 v6, 0x3d372713, v4
	v_mul_f32_e32 v6, v6, v4
	v_fma_f32 v6, v6, v4, v4
	v_mul_f32_e32 v6, 0xbfcc422a, v6
	v_add_f32_e32 v3, 1.0, v3
	v_mul_f32_e32 v6, 0x3fb8aa3b, v6
	v_rcp_f32_e32 v3, v3
	v_exp_f32_e32 v6, v6
	v_mul_f32_e32 v2, v11, v2
	v_fmac_f32_e32 v9, v17, v2
	v_cvt_pk_bf16_f32 v2, v9, s0
	ds_write_b16 v14, v2 offset:1840
	v_fma_f32 v2, v3, v27, -v10
	v_add_f32_e32 v3, 1.0, v6
	v_rcp_f32_e32 v3, v3
	v_mul_f32_e32 v2, v11, v2
	v_fma_f32 v2, v18, v2, v22
	v_lshlrev_b32_e32 v29, 16, v5
	v_cvt_pk_bf16_f32 v2, v2, s0
	ds_write_b16 v14, v2 offset:2112
	v_fma_f32 v2, v3, v4, -v10
	v_mul_f32_e32 v3, 0x3d372713, v29
	v_mul_f32_e32 v3, v3, v29
	v_fma_f32 v3, v3, v29, v29
	v_mul_f32_e32 v3, 0xbfcc422a, v3
	v_and_b32_e32 v5, 0xffff0000, v5
	v_mul_f32_e32 v3, 0x3fb8aa3b, v3
	v_exp_f32_e32 v3, v3
	v_mul_f32_e32 v4, 0x3d372713, v5
	v_mul_f32_e32 v4, v4, v5
	v_fma_f32 v4, v4, v5, v5
	v_mul_f32_e32 v4, 0xbfcc422a, v4
	v_add_f32_e32 v3, 1.0, v3
	v_mul_f32_e32 v4, 0x3fb8aa3b, v4
	v_rcp_f32_e32 v3, v3
	v_exp_f32_e32 v4, v4
	v_mul_f32_e32 v2, v11, v2
	v_fma_f32 v2, v19, v2, v23
	v_cvt_pk_bf16_f32 v2, v2, s0
	ds_write_b16 v14, v2 offset:2384
	v_fma_f32 v2, v3, v29, -v10
	v_add_f32_e32 v3, 1.0, v4
	v_rcp_f32_e32 v3, v3
	v_mul_f32_e32 v2, v11, v2
	v_fma_f32 v2, v20, v2, v24
	v_cvt_pk_bf16_f32 v2, v2, s0
	ds_write_b16 v14, v2 offset:2656
	v_fma_f32 v2, v3, v5, -v10
	v_mul_f32_e32 v2, v11, v2
	v_fmac_f32_e32 v25, v21, v2
	v_cvt_pk_bf16_f32 v2, v25, s0
	v_add_u32_e32 v3, v12, v169
	ds_write_b16 v3, v2 offset:1024
	v_mov_b64_e32 v[2:3], v[222:223]
	v_mov_b64_e32 v[4:5], v[224:225]
	v_lshl_add_u64 v[18:19], v[132:133], 0, s[72:73]
	v_lshl_add_u64 v[22:23], v[124:125], 0, s[72:73]
	global_load_dwordx4 v[6:9], v[22:23], off offset:-16
	global_load_dwordx4 v[14:17], v[18:19], off offset:-16
	s_nop 0
	global_load_dwordx4 v[18:21], v[18:19], off
	s_nop 0
	global_load_dwordx4 v[22:25], v[22:23], off
	s_nop 0
	global_load_dwordx4 v[62:65], v[142:143], off offset:-240
	global_load_dwordx4 v[58:61], v[142:143], off offset:-256
	global_load_dwordx4 v[50:53], v[142:143], off offset:-112
	global_load_dwordx4 v[54:57], v[142:143], off offset:-128
	global_load_dwordx4 v[42:45], v[142:143], off offset:16
	global_load_dwordx4 v[46:49], v[142:143], off
	global_load_dwordx4 v[34:37], v[142:143], off offset:144
	global_load_dwordx4 v[38:41], v[142:143], off offset:128
	s_waitcnt vmcnt(0) lgkmcnt(0)
	v_lshlrev_b32_e32 v13, 16, v2
	v_mul_f32_e32 v28, 0x3d372713, v13
	v_mul_f32_e32 v28, v28, v13
	v_fma_f32 v28, v28, v13, v13
	v_mul_f32_e32 v28, 0xbfcc422a, v28
	v_mul_f32_e32 v28, 0x3fb8aa3b, v28
	v_exp_f32_e32 v28, v28
	v_and_b32_e32 v2, 0xffff0000, v2
	v_mul_f32_e32 v30, 0x3d372713, v2
	v_mul_f32_e32 v30, v30, v2
	v_add_f32_e32 v28, 1.0, v28
	v_fma_f32 v30, v30, v2, v2
	v_rcp_f32_e32 v28, v28
	v_mul_f32_e32 v30, 0xbfcc422a, v30
	v_mul_f32_e32 v30, 0x3fb8aa3b, v30
	v_exp_f32_e32 v30, v30
	v_fma_f32 v13, v28, v13, -v10
	v_mul_f32_e32 v13, v11, v13
	v_fma_f32 v6, v14, v13, v6
	v_add_f32_e32 v13, 1.0, v30
	v_lshlrev_b32_e32 v26, 16, v3
	v_rcp_f32_e32 v13, v13
	v_cvt_pk_bf16_f32 v6, v6, s0
	v_add_u32_e32 v14, v12, v170
	ds_write_b16 v14, v6 offset:1024
	v_mul_f32_e32 v6, 0x3d372713, v26
	v_mul_f32_e32 v6, v6, v26
	v_fma_f32 v6, v6, v26, v26
	v_fma_f32 v2, v13, v2, -v10
	v_mul_f32_e32 v6, 0xbfcc422a, v6
	v_and_b32_e32 v3, 0xffff0000, v3
	v_mul_f32_e32 v6, 0x3fb8aa3b, v6
	v_mul_f32_e32 v2, v11, v2
	v_exp_f32_e32 v6, v6
	v_fma_f32 v2, v15, v2, v7
	v_mul_f32_e32 v7, 0x3d372713, v3
	v_mul_f32_e32 v7, v7, v3
	v_fma_f32 v7, v7, v3, v3
	v_mul_f32_e32 v7, 0xbfcc422a, v7
	v_add_f32_e32 v6, 1.0, v6
	v_mul_f32_e32 v7, 0x3fb8aa3b, v7
	v_rcp_f32_e32 v6, v6
	v_exp_f32_e32 v7, v7
	v_cvt_pk_bf16_f32 v2, v2, s0
	ds_write_b16 v14, v2 offset:1296
	v_fma_f32 v2, v6, v26, -v10
	v_add_f32_e32 v6, 1.0, v7
	v_rcp_f32_e32 v6, v6
	v_mul_f32_e32 v2, v11, v2
	v_fma_f32 v2, v16, v2, v8
	v_lshlrev_b32_e32 v27, 16, v4
	v_cvt_pk_bf16_f32 v2, v2, s0
	ds_write_b16 v14, v2 offset:1568
	v_fma_f32 v2, v6, v3, -v10
	v_mul_f32_e32 v3, 0x3d372713, v27
	v_mul_f32_e32 v3, v3, v27
	v_fma_f32 v3, v3, v27, v27
	v_mul_f32_e32 v3, 0xbfcc422a, v3
	v_and_b32_e32 v4, 0xffff0000, v4
	v_mul_f32_e32 v3, 0x3fb8aa3b, v3
	v_exp_f32_e32 v3, v3
	v_mul_f32_e32 v6, 0x3d372713, v4
	v_mul_f32_e32 v6, v6, v4
	v_fma_f32 v6, v6, v4, v4
	v_mul_f32_e32 v6, 0xbfcc422a, v6
	v_add_f32_e32 v3, 1.0, v3
	v_mul_f32_e32 v6, 0x3fb8aa3b, v6
	v_rcp_f32_e32 v3, v3
	v_exp_f32_e32 v6, v6
	v_mul_f32_e32 v2, v11, v2
	v_fmac_f32_e32 v9, v17, v2
	v_cvt_pk_bf16_f32 v2, v9, s0
	ds_write_b16 v14, v2 offset:1840
	v_fma_f32 v2, v3, v27, -v10
	v_add_f32_e32 v3, 1.0, v6
	v_rcp_f32_e32 v3, v3
	v_mul_f32_e32 v2, v11, v2
	v_fma_f32 v2, v18, v2, v22
	v_lshlrev_b32_e32 v29, 16, v5
	v_cvt_pk_bf16_f32 v2, v2, s0
	ds_write_b16 v14, v2 offset:2112
	v_fma_f32 v2, v3, v4, -v10
	v_mul_f32_e32 v3, 0x3d372713, v29
	v_mul_f32_e32 v3, v3, v29
	v_fma_f32 v3, v3, v29, v29
	v_mul_f32_e32 v3, 0xbfcc422a, v3
	v_and_b32_e32 v5, 0xffff0000, v5
	v_mul_f32_e32 v3, 0x3fb8aa3b, v3
	v_exp_f32_e32 v3, v3
	v_mul_f32_e32 v4, 0x3d372713, v5
	v_mul_f32_e32 v4, v4, v5
	v_fma_f32 v4, v4, v5, v5
	v_mul_f32_e32 v4, 0xbfcc422a, v4
	v_add_f32_e32 v3, 1.0, v3
	v_mul_f32_e32 v4, 0x3fb8aa3b, v4
	v_rcp_f32_e32 v3, v3
	v_exp_f32_e32 v4, v4
	v_mul_f32_e32 v2, v11, v2
	v_fma_f32 v2, v19, v2, v23
	v_cvt_pk_bf16_f32 v2, v2, s0
	ds_write_b16 v14, v2 offset:2384
	v_fma_f32 v2, v3, v29, -v10
	v_add_f32_e32 v3, 1.0, v4
	v_rcp_f32_e32 v3, v3
	v_mul_f32_e32 v2, v11, v2
	v_fma_f32 v2, v20, v2, v24
	v_cvt_pk_bf16_f32 v2, v2, s0
	ds_write_b16 v14, v2 offset:2656
	v_fma_f32 v2, v3, v5, -v10
	v_mul_f32_e32 v2, v11, v2
	v_fmac_f32_e32 v25, v21, v2
	v_cvt_pk_bf16_f32 v2, v25, s0
	v_add_u32_e32 v3, v12, v171
	ds_write_b16 v3, v2 offset:1024
	s_waitcnt lgkmcnt(0)
	s_barrier
	v_mov_b32_e32 v2, 0
	v_mov_b32_e32 v3, 0
	v_mov_b32_e32 v4, 0
	v_mov_b32_e32 v5, 0
	v_mov_b32_e32 v6, 0
	v_mov_b32_e32 v7, 0
	v_mov_b32_e32 v8, 0
	v_mov_b32_e32 v9, 0
	v_mov_b32_e32 v10, 0
	v_mov_b32_e32 v11, 0
	v_mov_b32_e32 v12, 0
	v_mov_b32_e32 v13, 0
	v_mov_b32_e32 v14, 0
	v_mov_b32_e32 v15, 0
	v_mov_b32_e32 v16, 0
	v_mov_b32_e32 v17, 0
	v_mov_b32_e32 v18, 0
	v_mov_b32_e32 v19, 0
	v_mov_b32_e32 v20, 0
	v_mov_b32_e32 v21, 0
	v_mov_b32_e32 v22, 0
	v_mov_b32_e32 v23, 0
	v_mov_b32_e32 v24, 0
	v_mov_b32_e32 v25, 0
	v_mov_b32_e32 v26, 0
	v_mov_b32_e32 v27, 0
	v_mov_b32_e32 v28, 0
	v_mov_b32_e32 v29, 0
	v_mov_b32_e32 v30, 0
	s_cbranch_vccnz .LBB0_123
	v_mov_b32_e32 v2, s89
	v_cndmask_b32_e64 v3, v60, v60, s[4:5]
	v_cndmask_b32_e64 v4, v61, v61, s[4:5]
	v_cndmask_b32_e64 v5, v58, v2, s[4:5]
	v_cndmask_b32_e64 v6, v62, v2, s[6:7]
	v_cndmask_b32_e64 v2, v65, v65, s[6:7]
	v_cndmask_b32_e64 v7, v64, v64, s[6:7]
	v_cndmask_b32_e64 v8, v63, v63, s[6:7]
	v_cndmask_b32_e64 v4, v4, v61, s[8:9]
	v_cndmask_b32_e64 v3, v3, v60, s[8:9]
	v_lshl_add_u32 v14, v163, 1, s37
	v_cndmask_b32_e64 v5, v5, v58, s[8:9]
	v_cndmask_b32_e64 v9, 0, v59, s[8:9]
	v_cndmask_b32_e64 v8, v8, 0, s[10:11]
	v_cndmask_b32_e64 v3, v3, 0, s[12:13]
	v_cndmask_b32_e64 v7, v7, 0, s[14:15]
	v_cndmask_b32_e64 v4, v4, 0, s[16:17]
	v_cndmask_b32_e64 v10, v2, 0, s[18:19]
	v_add_u32_e32 v59, v14, v172
	v_cvt_pk_bf16_f32 v2, v5, v9
	v_cvt_pk_bf16_f32 v3, v3, v4
	v_cvt_pk_bf16_f32 v4, v6, v8
	v_cvt_pk_bf16_f32 v5, v7, v10
	ds_read_b128 v[6:9], v59 offset:1024
	ds_read_b128 v[10:13], v59 offset:5376
	s_waitcnt lgkmcnt(1)
	v_mfma_f32_16x16x32_bf16 v[30:33], v[2:5], v[6:9], 0
	v_add_u32_e32 v60, v14, v173
	v_add_u32_e32 v58, v14, v174
	s_and_b64 vcc, exec, s[0:1]
	s_waitcnt lgkmcnt(0)
	v_mfma_f32_16x16x32_bf16 v[26:29], v[2:5], v[10:13], 0
	ds_read_b128 v[6:9], v59 offset:9728
	ds_read_b128 v[10:13], v59 offset:18432
	ds_read_b128 v[62:65], v58 offset:1024
	s_waitcnt lgkmcnt(2)
	v_mfma_f32_16x16x32_bf16 v[22:25], v[2:5], v[6:9], 0
	ds_read_b128 v[6:9], v60 offset:1024
	s_waitcnt lgkmcnt(0)
	v_mfma_f32_16x16x32_bf16 v[18:21], v[2:5], v[6:9], 0
	ds_read_b128 v[6:9], v59 offset:22784
	ds_read_b128 v[146:149], v59 offset:27136
	v_mfma_f32_16x16x32_bf16 v[14:17], v[2:5], v[10:13], 0
	s_waitcnt lgkmcnt(1)
	v_mfma_f32_16x16x32_bf16 v[10:13], v[2:5], v[6:9], 0
	s_waitcnt lgkmcnt(0)
	v_mfma_f32_16x16x32_bf16 v[6:9], v[2:5], v[146:149], 0
	v_mfma_f32_16x16x32_bf16 v[2:5], v[2:5], v[62:65], 0
	s_cbranch_vccz .LBB0_123
	v_mov_b32_e32 v62, s89
	v_cndmask_b32_e64 v61, v54, v62, s[20:21]
	v_mov_b32_e32 v54, s89
	v_cndmask_b32_e64 v57, v57, v57, s[20:21]
	v_cndmask_b32_e64 v56, v56, v56, s[20:21]
	v_cndmask_b32_e64 v55, v55, v55, s[20:21]
	v_cndmask_b32_e64 v54, v50, v54, s[22:23]
	v_cndmask_b32_e64 v50, v53, v53, s[22:23]
	v_cndmask_b32_e64 v52, v52, v52, s[22:23]
	v_cndmask_b32_e64 v51, v51, v51, s[22:23]
	v_cndmask_b32_e64 v53, v55, 0, s[24:25]
	v_cndmask_b32_e64 v55, v51, 0, s[26:27]
	v_cndmask_b32_e64 v51, v56, 0, s[28:29]
	v_cndmask_b32_e64 v56, v52, 0, s[38:39]
	v_cndmask_b32_e64 v52, v57, 0, s[40:41]
	v_cndmask_b32_e64 v57, v50, 0, s[42:43]
	v_cvt_pk_bf16_f32 v50, v61, v53
	v_cvt_pk_bf16_f32 v51, v51, v52
	v_cvt_pk_bf16_f32 v52, v54, v55
	v_cvt_pk_bf16_f32 v53, v56, v57
	ds_read_b128 v[54:57], v59 offset:1088
	s_andn2_b64 vcc, exec, s[82:83]
	s_waitcnt lgkmcnt(0)
	v_mfma_f32_16x16x32_bf16 v[30:33], v[50:53], v[54:57], v[30:33]
	ds_read_b128 v[54:57], v59 offset:5440
	s_waitcnt lgkmcnt(0)
	v_mfma_f32_16x16x32_bf16 v[26:29], v[50:53], v[54:57], v[26:29]
	ds_read_b128 v[54:57], v59 offset:9792
	s_waitcnt lgkmcnt(0)
	v_mfma_f32_16x16x32_bf16 v[22:25], v[50:53], v[54:57], v[22:25]
	ds_read_b128 v[54:57], v60 offset:1088
	s_waitcnt lgkmcnt(0)
	v_mfma_f32_16x16x32_bf16 v[18:21], v[50:53], v[54:57], v[18:21]
	ds_read_b128 v[54:57], v59 offset:18496
	s_waitcnt lgkmcnt(0)
	v_mfma_f32_16x16x32_bf16 v[14:17], v[50:53], v[54:57], v[14:17]
	ds_read_b128 v[54:57], v59 offset:22848
	s_waitcnt lgkmcnt(0)
	v_mfma_f32_16x16x32_bf16 v[10:13], v[50:53], v[54:57], v[10:13]
	ds_read_b128 v[54:57], v59 offset:27200
	s_waitcnt lgkmcnt(0)
	v_mfma_f32_16x16x32_bf16 v[6:9], v[50:53], v[54:57], v[6:9]
	ds_read_b128 v[54:57], v58 offset:1088
	s_waitcnt lgkmcnt(0)
	v_mfma_f32_16x16x32_bf16 v[2:5], v[50:53], v[54:57], v[2:5]
	s_cbranch_vccnz .LBB0_123
	v_mov_b32_e32 v50, s89
	v_readlane_b32 s56, v255, 49
	v_cndmask_b32_e64 v50, v46, v50, s[44:45]
	v_cndmask_b32_e64 v47, v47, v47, s[44:45]
	v_mov_b32_e32 v46, s89
	v_readlane_b32 s57, v255, 50
	v_cndmask_b32_e64 v46, v42, v46, s[46:47]
	v_cndmask_b32_e64 v42, v45, v45, s[46:47]
	v_cndmask_b32_e64 v45, v47, 0, s[56:57]
	v_readlane_b32 s56, v255, 25
	v_cndmask_b32_e64 v43, v43, v43, s[46:47]
	v_readlane_b32 s57, v255, 26
	v_cndmask_b32_e64 v48, v48, v48, s[44:45]
	v_cndmask_b32_e64 v44, v44, v44, s[46:47]
	v_cndmask_b32_e64 v47, v43, 0, s[56:57]
	v_readlane_b32 s56, v255, 29
	v_readlane_b32 s57, v255, 30
	v_cndmask_b32_e64 v49, v49, v49, s[44:45]
	s_andn2_b64 vcc, exec, s[84:85]
	v_cndmask_b32_e64 v43, v48, 0, s[56:57]
	v_readlane_b32 s56, v255, 15
	v_readlane_b32 s57, v255, 16
	s_nop 1
	v_cndmask_b32_e64 v48, v44, 0, s[56:57]
	v_readlane_b32 s56, v255, 19
	v_readlane_b32 s57, v255, 20
	s_nop 1
	v_cndmask_b32_e64 v44, v49, 0, s[56:57]
	v_readlane_b32 s56, v255, 33
	v_readlane_b32 s57, v255, 34
	v_cvt_pk_bf16_f32 v43, v43, v44
	v_cvt_pk_bf16_f32 v44, v46, v47
	v_cndmask_b32_e64 v49, v42, 0, s[56:57]
	v_cvt_pk_bf16_f32 v42, v50, v45
	v_cvt_pk_bf16_f32 v45, v48, v49
	ds_read_b128 v[46:49], v59 offset:1152
	s_waitcnt lgkmcnt(0)
	v_mfma_f32_16x16x32_bf16 v[30:33], v[42:45], v[46:49], v[30:33]
	ds_read_b128 v[46:49], v59 offset:5504
	s_waitcnt lgkmcnt(0)
	v_mfma_f32_16x16x32_bf16 v[26:29], v[42:45], v[46:49], v[26:29]
	ds_read_b128 v[46:49], v59 offset:9856
	s_waitcnt lgkmcnt(0)
	v_mfma_f32_16x16x32_bf16 v[22:25], v[42:45], v[46:49], v[22:25]
	ds_read_b128 v[46:49], v60 offset:1152
	s_waitcnt lgkmcnt(0)
	v_mfma_f32_16x16x32_bf16 v[18:21], v[42:45], v[46:49], v[18:21]
	ds_read_b128 v[46:49], v59 offset:18560
	s_waitcnt lgkmcnt(0)
	v_mfma_f32_16x16x32_bf16 v[14:17], v[42:45], v[46:49], v[14:17]
	ds_read_b128 v[46:49], v59 offset:22912
	s_waitcnt lgkmcnt(0)
	v_mfma_f32_16x16x32_bf16 v[10:13], v[42:45], v[46:49], v[10:13]
	ds_read_b128 v[46:49], v59 offset:27264
	s_waitcnt lgkmcnt(0)
	v_mfma_f32_16x16x32_bf16 v[6:9], v[42:45], v[46:49], v[6:9]
	ds_read_b128 v[46:49], v58 offset:1152
	s_waitcnt lgkmcnt(0)
	v_mfma_f32_16x16x32_bf16 v[2:5], v[42:45], v[46:49], v[2:5]
	s_cbranch_vccnz .LBB0_123
	v_mov_b32_e32 v42, s89
	v_readlane_b32 s56, v255, 39
	v_cndmask_b32_e64 v42, v38, v42, s[76:77]
	v_cndmask_b32_e64 v39, v39, v39, s[76:77]
	v_mov_b32_e32 v38, s89
	v_readlane_b32 s57, v255, 40
	v_cndmask_b32_e64 v38, v34, v38, s[78:79]
	v_cndmask_b32_e64 v34, v37, v37, s[78:79]
	v_cndmask_b32_e64 v37, v39, 0, s[56:57]
	v_readlane_b32 s56, v255, 41
	v_cndmask_b32_e64 v35, v35, v35, s[78:79]
	v_readlane_b32 s57, v255, 42
	v_cndmask_b32_e64 v40, v40, v40, s[76:77]
	v_cndmask_b32_e64 v36, v36, v36, s[78:79]
	v_cndmask_b32_e64 v39, v35, 0, s[56:57]
	v_readlane_b32 s56, v255, 45
	v_readlane_b32 s57, v255, 46
	v_cndmask_b32_e64 v41, v41, v41, s[76:77]
	s_nop 0
	v_cndmask_b32_e64 v35, v40, 0, s[56:57]
	v_readlane_b32 s56, v255, 9
	v_readlane_b32 s57, v255, 10
	s_nop 1
	v_cndmask_b32_e64 v40, v36, 0, s[56:57]
	v_readlane_b32 s56, v255, 11
	v_readlane_b32 s57, v255, 12
	s_nop 1
	v_cndmask_b32_e64 v36, v41, 0, s[56:57]
	v_readlane_b32 s56, v255, 13
	v_readlane_b32 s57, v255, 14
	v_cvt_pk_bf16_f32 v35, v35, v36
	v_cvt_pk_bf16_f32 v36, v38, v39
	v_cndmask_b32_e64 v41, v34, 0, s[56:57]
	v_cvt_pk_bf16_f32 v34, v42, v37
	v_cvt_pk_bf16_f32 v37, v40, v41
	ds_read_b128 v[38:41], v59 offset:1216
	s_waitcnt lgkmcnt(0)
	v_mfma_f32_16x16x32_bf16 v[30:33], v[34:37], v[38:41], v[30:33]
	ds_read_b128 v[38:41], v59 offset:5568
	s_waitcnt lgkmcnt(0)
	v_mfma_f32_16x16x32_bf16 v[26:29], v[34:37], v[38:41], v[26:29]
	ds_read_b128 v[38:41], v59 offset:9920
	s_waitcnt lgkmcnt(0)
	v_mfma_f32_16x16x32_bf16 v[22:25], v[34:37], v[38:41], v[22:25]
	ds_read_b128 v[38:41], v60 offset:1216
	s_waitcnt lgkmcnt(0)
	v_mfma_f32_16x16x32_bf16 v[18:21], v[34:37], v[38:41], v[18:21]
	ds_read_b128 v[38:41], v59 offset:18624
	s_waitcnt lgkmcnt(0)
	v_mfma_f32_16x16x32_bf16 v[14:17], v[34:37], v[38:41], v[14:17]
	ds_read_b128 v[38:41], v59 offset:22976
	s_waitcnt lgkmcnt(0)
	v_mfma_f32_16x16x32_bf16 v[10:13], v[34:37], v[38:41], v[10:13]
	ds_read_b128 v[38:41], v59 offset:27328
	s_waitcnt lgkmcnt(0)
	v_mfma_f32_16x16x32_bf16 v[6:9], v[34:37], v[38:41], v[6:9]
	ds_read_b128 v[38:41], v58 offset:1216
	s_waitcnt lgkmcnt(0)
	v_mfma_f32_16x16x32_bf16 v[2:5], v[34:37], v[38:41], v[2:5]
	s_branch .LBB0_123
